# attention accumulator-rescale v_pk_mul_f32 ops between MFMAs split into scalar v_mul_f32 pairs (guide 7.5)
# speedup vs baseline: 1.0077x; 1.0077x over previous
; __device__ __forceinline__ void attn_na(unsigned char* lds, const int unit, const bf16_t* __restrict__ QKG, const bf16_t* __restrict__ Vt, bf16_t* __restrict__ Oout, const float* __restrict__ btab) {
;     ...
;             for (int d0 = 0; d0 < 8; ++d0) {
;                 const bf16x8 k0 = *(const bf16x8*)(Kh + ka_off + d0 * 32);
;                 p0 = __builtin_amdgcn_mfma_f32_32x32x16_bf16(k0, qf[d0], p0, 0, 0, 0);
;             }
;             const bool rowok = krow >= rsq && krow < rsq + 8;
;             const float* trp = tab + (rowok ? (krow - rq + 7) * 31 + 16 : TAB_SENT) + lanepart;
; #pragma unroll
;             for (int r = 0; r < 16; ++r) p0[r] = (p0[r] + trp[16 * (r >> 3) + (r & 7)]) + addmask[r];
;             float mx = p0[0];
; #pragma unroll
;             for (int r = 1; r < 16; ++r) mx = fmaxf(mx, p0[r]);
;             mx = fmaxf(mx, __shfl_xor(mx, 32));
;             if (__any(mx > m_run + THR)) { const float mnew = fmaxf(m_run, mx), alpha = __builtin_amdgcn_exp2f(m_run - mnew); m_run = mnew; l_run *= alpha;
; #pragma unroll
;                 for (int i = 0; i < 4; ++i)
; #pragma unroll
;                     for (int r = 0; r < 16; ++r) o[i][r] *= alpha; }
.LBB0_597:
	v_add_u32_e32 v68, s0, v171
	s_add_i32 s0, s11, s1
	s_add_i32 s18, s6, s10
	s_add_i32 s19, s10, -1
	v_add_u32_e32 v182, s0, v172
	s_add_i32 s0, s18, -1
	s_cmp_lt_i32 s19, s7
	s_cselect_b64 s[20:21], -1, 0
	s_cmp_le_u32 s16, s0
	s_cselect_b64 s[26:27], -1, 0
	s_or_b64 s[26:27], s[12:13], s[26:27]
	s_and_b64 s[20:21], s[20:21], s[26:27]
	s_cmp_lt_u32 s0, s17
	s_cselect_b64 s[26:27], -1, 0
	s_and_b64 s[20:21], s[20:21], s[26:27]
	s_andn2_b64 vcc, exec, s[20:21]
	v_add_u32_e32 v184, v68, v152
	s_cbranch_vccnz .LBB0_601
	ds_read_b128 v[214:217], v184
	ds_read_b128 v[218:221], v184 offset:32
	ds_read_b128 v[222:225], v184 offset:64
	ds_read_b128 v[226:229], v184 offset:96
	ds_read_b128 v[230:233], v184 offset:128
	ds_read_b128 v[234:237], v184 offset:160
	ds_read_b128 v[238:241], v184 offset:192
	ds_read_b128 v[242:245], v184 offset:224
	v_cmp_ge_u32_e32 vcc, s0, v173
	v_cmp_lt_u32_e64 s[0:1], s0, v176
	s_and_b64 vcc, vcc, s[0:1]
	v_subrev_u32_e32 v185, 31, v177
	s_nop 1
	v_cndmask_b32_e32 v185, v209, v185, vcc
	v_lshl_add_u32 v192, v185, 2, v175
	s_waitcnt lgkmcnt(7)
	v_mfma_f32_32x32x16_bf16 v[68:83], v[214:217], v[84:87], 0
	s_waitcnt lgkmcnt(6)
	v_mfma_f32_32x32x16_bf16 v[68:83], v[218:221], v[88:91], v[68:83]
	s_waitcnt lgkmcnt(5)
	v_mfma_f32_32x32x16_bf16 v[68:83], v[222:225], v[92:95], v[68:83]
	s_waitcnt lgkmcnt(4)
	v_mfma_f32_32x32x16_bf16 v[68:83], v[226:229], v[96:99], v[68:83]
	ds_read2_b32 v[214:215], v192 offset0:15 offset1:16
	ds_read2_b32 v[216:217], v192 offset0:17 offset1:18
	ds_read2_b32 v[218:219], v192 offset0:19 offset1:20
	ds_read2_b32 v[220:221], v192 offset0:21 offset1:22
	ds_read2_b32 v[222:223], v192 offset0:31 offset1:32
	ds_read2_b32 v[224:225], v192 offset0:33 offset1:34
	ds_read2_b32 v[226:227], v192 offset0:35 offset1:36
	ds_read2_b32 v[228:229], v192 offset0:37 offset1:38
	s_waitcnt lgkmcnt(11)
	v_mfma_f32_32x32x16_bf16 v[68:83], v[230:233], v[100:103], v[68:83]
	s_waitcnt lgkmcnt(10)
	v_mfma_f32_32x32x16_bf16 v[68:83], v[234:237], v[104:107], v[68:83]
	s_waitcnt lgkmcnt(9)
	v_mfma_f32_32x32x16_bf16 v[68:83], v[238:241], v[108:111], v[68:83]
	s_waitcnt lgkmcnt(8)
	v_mfma_f32_32x32x16_bf16 v[68:83], v[242:245], v[112:115], v[68:83]
	s_waitcnt lgkmcnt(0)
	s_nop 10
	v_add_f32_e32 v68, v68, v214
	v_add_f32_e32 v191, v67, v68
	v_add_f32_e32 v68, v69, v215
	v_add_f32_e32 v189, v151, v68
	v_add_f32_e32 v68, v70, v216
	v_add_f32_e32 v190, v153, v68
	v_add_f32_e32 v68, v71, v217
	v_add_f32_e32 v187, v158, v68
	v_add_f32_e32 v68, v72, v218
	v_add_f32_e32 v188, v159, v68
	v_add_f32_e32 v68, v73, v219
	v_add_f32_e32 v185, v160, v68
	v_add_f32_e32 v68, v74, v220
	v_add_f32_e32 v186, v161, v68
	v_add_f32_e32 v68, v75, v221
	v_add_f32_e32 v75, v162, v68
	v_add_f32_e32 v68, v76, v222
	v_add_f32_e32 v76, v163, v68
	v_add_f32_e32 v68, v77, v223
	v_add_f32_e32 v73, v164, v68
	v_max_f32_e32 v77, v191, v189
	v_max3_f32 v77, v77, v190, v187
	v_max3_f32 v77, v77, v188, v185
	v_max3_f32 v77, v77, v186, v75
	v_add_f32_e32 v68, v78, v224
	v_add_f32_e32 v74, v165, v68
	v_add_f32_e32 v68, v79, v225
	v_add_f32_e32 v71, v166, v68
	v_max3_f32 v77, v77, v76, v73
	v_max3_f32 v77, v77, v74, v71
	v_add_f32_e32 v68, v80, v226
	v_add_f32_e32 v72, v167, v68
	v_add_f32_e32 v68, v81, v227
	v_add_f32_e32 v69, v168, v68
	v_add_f32_e32 v68, v82, v228
	v_add_f32_e32 v70, v169, v68
	v_add_f32_e32 v68, v83, v229
	v_and_b32_e32 v79, 64, v206
	v_xor_b32_e32 v78, 32, v206
	v_add_u32_e32 v79, 64, v79
	v_cmp_lt_i32_e32 vcc, v78, v79
	v_add_f32_e32 v68, v170, v68
	v_max3_f32 v77, v77, v72, v69
	v_cndmask_b32_e32 v78, v206, v78, vcc
	v_max3_f32 v77, v77, v70, v68
	v_lshlrev_b32_e32 v78, 2, v78
	ds_bpermute_b32 v78, v78, v77
	s_waitcnt lgkmcnt(0)
	v_max_f32_e32 v78, v78, v78
	v_max_f32_e32 v77, v77, v78
	v_add_f32_e32 v78, 0x41000000, v183
	v_cmp_gt_f32_e32 vcc, v77, v78
	s_cbranch_vccz .LBB0_600
	v_max_f32_e32 v77, v77, v77
	v_max_f32_e32 v78, v183, v183
	v_max_f32_e32 v77, v78, v77
	v_sub_f32_e32 v78, v183, v77
	v_exp_f32_e32 v78, v78
	v_mov_b32_e32 v183, v77
	v_mul_f32_e32 v64, v78, v64
	v_mul_f32_e32 v65, v78, v65
	v_mul_f32_e32 v62, v78, v62
	v_mul_f32_e32 v63, v78, v63
	v_mul_f32_e32 v60, v78, v60
	v_mul_f32_e32 v61, v78, v61
	v_mul_f32_e32 v58, v78, v58
	v_mul_f32_e32 v59, v78, v59
	v_mul_f32_e32 v56, v78, v56
	v_mul_f32_e32 v57, v78, v57
	v_mul_f32_e32 v54, v78, v54
	v_mul_f32_e32 v55, v78, v55
	v_mul_f32_e32 v52, v78, v52
	v_mul_f32_e32 v53, v78, v53
	v_mul_f32_e32 v50, v78, v50
	v_mul_f32_e32 v51, v78, v51
	v_mul_f32_e32 v48, v78, v48
	v_mul_f32_e32 v49, v78, v49
	v_mul_f32_e32 v46, v78, v46
	v_mul_f32_e32 v47, v78, v47
	v_mul_f32_e32 v44, v78, v44
	v_mul_f32_e32 v45, v78, v45
	v_mul_f32_e32 v42, v78, v42
	v_mul_f32_e32 v43, v78, v43
	v_mul_f32_e32 v40, v78, v40
	v_mul_f32_e32 v41, v78, v41
	v_mul_f32_e32 v38, v78, v38
	v_mul_f32_e32 v39, v78, v39
	v_mul_f32_e32 v36, v78, v36
	v_mul_f32_e32 v37, v78, v37
	v_mul_f32_e32 v34, v78, v34
	v_mul_f32_e32 v35, v78, v35
	v_mul_f32_e32 v32, v78, v32
	v_mul_f32_e32 v33, v78, v33
	v_mul_f32_e32 v30, v78, v30
	v_mul_f32_e32 v31, v78, v31
	v_mul_f32_e32 v28, v78, v28
	v_mul_f32_e32 v29, v78, v29
	v_mul_f32_e32 v26, v78, v26
	v_mul_f32_e32 v27, v78, v27
	v_mul_f32_e32 v24, v78, v24
	v_mul_f32_e32 v25, v78, v25
	v_mul_f32_e32 v22, v78, v22
	v_mul_f32_e32 v23, v78, v23
	v_mul_f32_e32 v20, v78, v20
	v_mul_f32_e32 v21, v78, v21
	v_mul_f32_e32 v18, v78, v18
	v_mul_f32_e32 v19, v78, v19
	v_mul_f32_e32 v16, v78, v16
	v_mul_f32_e32 v17, v78, v17
	v_mul_f32_e32 v14, v78, v14
	v_mul_f32_e32 v15, v78, v15
	v_mul_f32_e32 v12, v78, v12
	v_mul_f32_e32 v13, v78, v13
	v_mul_f32_e32 v10, v78, v10
	v_mul_f32_e32 v11, v78, v11
	v_mul_f32_e32 v8, v78, v8
	v_mul_f32_e32 v9, v78, v9
	v_mul_f32_e32 v6, v78, v6
	v_mul_f32_e32 v7, v78, v7
	v_mul_f32_e32 v4, v78, v4
	v_mul_f32_e32 v5, v78, v5
	v_mul_f32_e32 v2, v78, v2
	v_mul_f32_e32 v3, v78, v3
	v_mul_f32_e32 v66, v66, v78

; __device__ __forceinline__ void attn_na(unsigned char* lds, const int unit, const bf16_t* __restrict__ QKG, const bf16_t* __restrict__ Vt, bf16_t* __restrict__ Oout, const float* __restrict__ btab) {
;     ...
;             for (int d0 = 0; d0 < 8; ++d0) {
;                 const bf16x8 k0 = *(const bf16x8*)(Kh + ka_off + d0 * 32);
;                 p0 = __builtin_amdgcn_mfma_f32_32x32x16_bf16(k0, qf[d0], p0, 0, 0, 0);
;             }
;             const bool rowok = krow >= rsq && krow < rsq + 8;
;             const float* trp = tab + (rowok ? (krow - rq + 7) * 31 + 16 : TAB_SENT) + lanepart;
; #pragma unroll
;             for (int r = 0; r < 16; ++r) p0[r] = (p0[r] + trp[16 * (r >> 3) + (r & 7)]) + addmask[r];
;             float mx = p0[0];
; #pragma unroll
;             for (int r = 1; r < 16; ++r) mx = fmaxf(mx, p0[r]);
;             mx = fmaxf(mx, __shfl_xor(mx, 32));
;             if (__any(mx > m_run + THR)) { const float mnew = fmaxf(m_run, mx), alpha = __builtin_amdgcn_exp2f(m_run - mnew); m_run = mnew; l_run *= alpha;
; #pragma unroll
;                 for (int i = 0; i < 4; ++i)
; #pragma unroll
;                     for (int r = 0; r < 16; ++r) o[i][r] *= alpha; }
.LBB0_601:
	s_cmp_lt_i32 s10, s7
	s_cselect_b64 s[0:1], -1, 0
	s_cmp_le_u32 s16, s18
	s_cselect_b64 s[20:21], -1, 0
	s_or_b64 s[20:21], s[12:13], s[20:21]
	s_and_b64 s[0:1], s[0:1], s[20:21]
	s_cmp_lt_u32 s18, s17
	s_cselect_b64 s[20:21], -1, 0
	s_and_b64 s[0:1], s[0:1], s[20:21]
	s_andn2_b64 vcc, exec, s[0:1]
	s_cbranch_vccnz .LBB0_594
	ds_read_b128 v[214:217], v184 offset:17408
	ds_read_b128 v[218:221], v184 offset:17440
	ds_read_b128 v[222:225], v184 offset:17472
	ds_read_b128 v[226:229], v184 offset:17504
	ds_read_b128 v[230:233], v184 offset:17536
	ds_read_b128 v[234:237], v184 offset:17568
	ds_read_b128 v[238:241], v184 offset:17600
	ds_read_b128 v[242:245], v184 offset:17632
	v_cmp_ge_u32_e32 vcc, s18, v173
	v_cmp_lt_u32_e64 s[0:1], s18, v176
	s_and_b64 vcc, vcc, s[0:1]
	s_nop 1
	v_cndmask_b32_e32 v246, v209, v177, vcc
	v_lshl_add_u32 v191, v246, 2, v175
	s_waitcnt lgkmcnt(7)
	v_mfma_f32_32x32x16_bf16 v[68:83], v[214:217], v[84:87], 0
	s_waitcnt lgkmcnt(6)
	v_mfma_f32_32x32x16_bf16 v[68:83], v[218:221], v[88:91], v[68:83]
	s_waitcnt lgkmcnt(5)
	v_mfma_f32_32x32x16_bf16 v[68:83], v[222:225], v[92:95], v[68:83]
	s_waitcnt lgkmcnt(4)
	v_mfma_f32_32x32x16_bf16 v[68:83], v[226:229], v[96:99], v[68:83]
	ds_read2_b32 v[214:215], v191 offset0:15 offset1:16
	ds_read2_b32 v[216:217], v191 offset0:17 offset1:18
	ds_read2_b32 v[218:219], v191 offset0:19 offset1:20
	ds_read2_b32 v[220:221], v191 offset0:21 offset1:22
	ds_read2_b32 v[222:223], v191 offset0:31 offset1:32
	ds_read2_b32 v[224:225], v191 offset0:33 offset1:34
	ds_read2_b32 v[226:227], v191 offset0:35 offset1:36
	ds_read2_b32 v[228:229], v191 offset0:37 offset1:38
	s_waitcnt lgkmcnt(11)
	v_mfma_f32_32x32x16_bf16 v[68:83], v[230:233], v[100:103], v[68:83]
	s_waitcnt lgkmcnt(10)
	v_mfma_f32_32x32x16_bf16 v[68:83], v[234:237], v[104:107], v[68:83]
	s_waitcnt lgkmcnt(9)
	v_mfma_f32_32x32x16_bf16 v[68:83], v[238:241], v[108:111], v[68:83]
	s_waitcnt lgkmcnt(8)
	v_mfma_f32_32x32x16_bf16 v[68:83], v[242:245], v[112:115], v[68:83]
	s_waitcnt lgkmcnt(0)
	s_nop 10
	v_add_f32_e32 v68, v68, v214
	v_add_f32_e32 v190, v67, v68
	v_add_f32_e32 v68, v69, v215
	v_add_f32_e32 v188, v151, v68
	v_add_f32_e32 v68, v70, v216
	v_add_f32_e32 v189, v153, v68
	v_add_f32_e32 v68, v71, v217
	v_add_f32_e32 v186, v158, v68
	v_add_f32_e32 v68, v72, v218
	v_add_f32_e32 v187, v159, v68
	v_add_f32_e32 v68, v73, v219
	v_add_f32_e32 v184, v160, v68
	v_add_f32_e32 v68, v74, v220
	v_add_f32_e32 v185, v161, v68
	v_add_f32_e32 v68, v75, v221
	v_add_f32_e32 v75, v162, v68
	v_add_f32_e32 v68, v76, v222
	v_add_f32_e32 v76, v163, v68
	v_add_f32_e32 v68, v77, v223
	v_add_f32_e32 v73, v164, v68
	v_max_f32_e32 v77, v190, v188
	v_max3_f32 v77, v77, v189, v186
	v_max3_f32 v77, v77, v187, v184
	v_max3_f32 v77, v77, v185, v75
	v_add_f32_e32 v68, v78, v224
	v_add_f32_e32 v74, v165, v68
	v_add_f32_e32 v68, v79, v225
	v_add_f32_e32 v71, v166, v68
	v_max3_f32 v77, v77, v76, v73
	v_max3_f32 v77, v77, v74, v71
	v_add_f32_e32 v68, v80, v226
	v_add_f32_e32 v72, v167, v68
	v_add_f32_e32 v68, v81, v227
	v_add_f32_e32 v69, v168, v68
	v_add_f32_e32 v68, v82, v228
	v_add_f32_e32 v70, v169, v68
	v_add_f32_e32 v68, v83, v229
	v_and_b32_e32 v79, 64, v206
	v_xor_b32_e32 v78, 32, v206
	v_add_u32_e32 v79, 64, v79
	v_cmp_lt_i32_e32 vcc, v78, v79
	v_add_f32_e32 v68, v170, v68
	v_max3_f32 v77, v77, v72, v69
	v_cndmask_b32_e32 v78, v206, v78, vcc
	v_max3_f32 v77, v77, v70, v68
	v_lshlrev_b32_e32 v78, 2, v78
	ds_bpermute_b32 v78, v78, v77
	s_waitcnt lgkmcnt(0)
	v_max_f32_e32 v78, v78, v78
	v_max_f32_e32 v77, v77, v78
	v_add_f32_e32 v78, 0x41000000, v183
	v_cmp_gt_f32_e32 vcc, v77, v78
	s_cbranch_vccz .LBB0_593
	v_max_f32_e32 v77, v77, v77
	v_max_f32_e32 v78, v183, v183
	v_max_f32_e32 v77, v78, v77
	v_sub_f32_e32 v78, v183, v77
	v_exp_f32_e32 v78, v78
	v_mov_b32_e32 v183, v77
	v_mul_f32_e32 v64, v78, v64
	v_mul_f32_e32 v65, v78, v65
	v_mul_f32_e32 v62, v78, v62
	v_mul_f32_e32 v63, v78, v63
	v_mul_f32_e32 v60, v78, v60
	v_mul_f32_e32 v61, v78, v61
	v_mul_f32_e32 v58, v78, v58
	v_mul_f32_e32 v59, v78, v59
	v_mul_f32_e32 v56, v78, v56
	v_mul_f32_e32 v57, v78, v57
	v_mul_f32_e32 v54, v78, v54
	v_mul_f32_e32 v55, v78, v55
	v_mul_f32_e32 v52, v78, v52
	v_mul_f32_e32 v53, v78, v53
	v_mul_f32_e32 v50, v78, v50
	v_mul_f32_e32 v51, v78, v51
	v_mul_f32_e32 v48, v78, v48
	v_mul_f32_e32 v49, v78, v49
	v_mul_f32_e32 v46, v78, v46
	v_mul_f32_e32 v47, v78, v47
	v_mul_f32_e32 v44, v78, v44
	v_mul_f32_e32 v45, v78, v45
	v_mul_f32_e32 v42, v78, v42
	v_mul_f32_e32 v43, v78, v43
	v_mul_f32_e32 v40, v78, v40
	v_mul_f32_e32 v41, v78, v41
	v_mul_f32_e32 v38, v78, v38
	v_mul_f32_e32 v39, v78, v39
	v_mul_f32_e32 v36, v78, v36
	v_mul_f32_e32 v37, v78, v37
	v_mul_f32_e32 v34, v78, v34
	v_mul_f32_e32 v35, v78, v35
	v_mul_f32_e32 v32, v78, v32
	v_mul_f32_e32 v33, v78, v33
	v_mul_f32_e32 v30, v78, v30
	v_mul_f32_e32 v31, v78, v31
	v_mul_f32_e32 v28, v78, v28
	v_mul_f32_e32 v29, v78, v29
	v_mul_f32_e32 v26, v78, v26
	v_mul_f32_e32 v27, v78, v27
	v_mul_f32_e32 v24, v78, v24
	v_mul_f32_e32 v25, v78, v25
	v_mul_f32_e32 v22, v78, v22
	v_mul_f32_e32 v23, v78, v23
	v_mul_f32_e32 v20, v78, v20
	v_mul_f32_e32 v21, v78, v21
	v_mul_f32_e32 v18, v78, v18
	v_mul_f32_e32 v19, v78, v19
	v_mul_f32_e32 v16, v78, v16
	v_mul_f32_e32 v17, v78, v17
	v_mul_f32_e32 v14, v78, v14
	v_mul_f32_e32 v15, v78, v15
	v_mul_f32_e32 v12, v78, v12
	v_mul_f32_e32 v13, v78, v13
	v_mul_f32_e32 v10, v78, v10
	v_mul_f32_e32 v11, v78, v11
	v_mul_f32_e32 v8, v78, v8
	v_mul_f32_e32 v9, v78, v9
	v_mul_f32_e32 v6, v78, v6
	v_mul_f32_e32 v7, v78, v7
	v_mul_f32_e32 v4, v78, v4
	v_mul_f32_e32 v5, v78, v5
	v_mul_f32_e32 v2, v78, v2
	v_mul_f32_e32 v3, v78, v3
	v_mul_f32_e32 v66, v66, v78
	s_branch .LBB0_593

; __device__ __forceinline__ void attn_win(unsigned char* lds, const int unit, const bf16_t* __restrict__ QKG, const bf16_t* __restrict__ Vt, bf16_t* __restrict__ Oout, const float* __restrict__ sink) {
;     ...
;         float mx = fmaxf(p0[0], p1[0]);
; #pragma unroll
;         for (int r = 1; r < 16; ++r) mx = fmaxf(mx, fmaxf(p0[r], p1[r]));
;         mx = fmaxf(mx, __shfl_xor(mx, 32));
;         if (__any(mx > m_run + THR)) { const float mnew = fmaxf(m_run, mx), alpha = __builtin_amdgcn_exp2f(m_run - mnew); m_run = mnew; l_run *= alpha;
; #pragma unroll
;             for (int i = 0; i < 4; ++i)
; #pragma unroll
;                 for (int r = 0; r < 16; ++r) o[i][r] *= alpha; }
.LBB0_616:
	s_nop 10
	v_max_f32_e32 v2, v81, v81
	v_max_f32_e32 v3, v97, v97
	v_max_f32_e32 v2, v3, v2
	v_max_f32_e32 v3, v82, v82
	v_max_f32_e32 v4, v98, v98
	v_max_f32_e32 v3, v4, v3
	v_max_f32_e32 v4, v83, v83
	v_max_f32_e32 v5, v99, v99
	v_max3_f32 v2, v96, v80, v2
	v_max_f32_e32 v4, v5, v4
	v_max3_f32 v2, v2, v3, v4
	v_max_f32_e32 v3, v84, v84
	v_max_f32_e32 v4, v100, v100
	v_max_f32_e32 v3, v4, v3
	v_max_f32_e32 v4, v85, v85
	v_max_f32_e32 v5, v101, v101
	v_max_f32_e32 v4, v5, v4
	v_max3_f32 v2, v2, v3, v4
	v_max_f32_e32 v3, v86, v86
	v_max_f32_e32 v4, v102, v102
	v_max_f32_e32 v3, v4, v3
	v_max_f32_e32 v4, v87, v87
	v_max_f32_e32 v5, v103, v103
	v_max_f32_e32 v4, v5, v4
	v_max3_f32 v2, v2, v3, v4
	v_max_f32_e32 v3, v88, v88
	v_max_f32_e32 v4, v104, v104
	v_max_f32_e32 v3, v4, v3
	v_max_f32_e32 v4, v89, v89
	v_max_f32_e32 v5, v105, v105
	v_max_f32_e32 v4, v5, v4
	v_max3_f32 v2, v2, v3, v4
	v_max_f32_e32 v3, v90, v90
	v_max_f32_e32 v4, v106, v106
	v_max_f32_e32 v3, v4, v3
	v_max_f32_e32 v4, v91, v91
	v_max_f32_e32 v5, v107, v107
	v_max_f32_e32 v4, v5, v4
	v_max3_f32 v2, v2, v3, v4
	v_max_f32_e32 v3, v92, v92
	v_max_f32_e32 v4, v108, v108
	v_max_f32_e32 v3, v4, v3
	v_max_f32_e32 v4, v93, v93
	v_max_f32_e32 v5, v109, v109
	v_max_f32_e32 v4, v5, v4
	v_max3_f32 v2, v2, v3, v4
	v_max_f32_e32 v3, v94, v94
	v_max_f32_e32 v4, v110, v110
	v_max_f32_e32 v3, v4, v3
	v_max_f32_e32 v4, v95, v95
	v_max_f32_e32 v5, v111, v111
	v_max_f32_e32 v4, v5, v4
	v_max3_f32 v2, v2, v3, v4
	v_and_b32_e32 v4, 64, v206
	v_xor_b32_e32 v3, 32, v206
	v_add_u32_e32 v4, 64, v4
	v_cmp_lt_i32_e32 vcc, v3, v4
	s_nop 1
	v_cndmask_b32_e32 v3, v206, v3, vcc
	v_lshlrev_b32_e32 v3, 2, v3
	ds_bpermute_b32 v3, v3, v2
	s_waitcnt lgkmcnt(0)
	v_max_f32_e32 v3, v3, v3
	v_max_f32_e32 v2, v2, v3
	v_add_f32_e32 v3, 0x41000000, v195
	v_cmp_gt_f32_e32 vcc, v2, v3
	s_cbranch_vccz .LBB0_618
	v_max_f32_e32 v2, v2, v2
	v_max_f32_e32 v3, v195, v195
	v_max_f32_e32 v3, v3, v2
	v_sub_f32_e32 v2, v195, v3
	v_exp_f32_e32 v2, v2
	v_mov_b32_e32 v195, v3
	v_mul_f32_e32 v78, v2, v78
	v_mul_f32_e32 v79, v2, v79
	v_mul_f32_e32 v76, v2, v76
	v_mul_f32_e32 v77, v2, v77
	v_mul_f32_e32 v74, v2, v74
	v_mul_f32_e32 v75, v2, v75
	v_mul_f32_e32 v72, v2, v72
	v_mul_f32_e32 v73, v2, v73
	v_mul_f32_e32 v70, v2, v70
	v_mul_f32_e32 v71, v2, v71
	v_mul_f32_e32 v68, v2, v68
	v_mul_f32_e32 v69, v2, v69
	v_mul_f32_e32 v66, v2, v66
	v_mul_f32_e32 v67, v2, v67
	v_mul_f32_e32 v64, v2, v64
	v_mul_f32_e32 v65, v2, v65
	v_mul_f32_e32 v62, v2, v62
	v_mul_f32_e32 v63, v2, v63
	v_mul_f32_e32 v60, v2, v60
	v_mul_f32_e32 v61, v2, v61
	v_mul_f32_e32 v58, v2, v58
	v_mul_f32_e32 v59, v2, v59
	v_mul_f32_e32 v56, v2, v56
	v_mul_f32_e32 v57, v2, v57
	v_mul_f32_e32 v54, v2, v54
	v_mul_f32_e32 v55, v2, v55
	v_mul_f32_e32 v52, v2, v52
	v_mul_f32_e32 v53, v2, v53
	v_mul_f32_e32 v50, v2, v50
	v_mul_f32_e32 v51, v2, v51
	v_mul_f32_e32 v48, v2, v48
	v_mul_f32_e32 v49, v2, v49
	v_mul_f32_e32 v46, v2, v46
	v_mul_f32_e32 v47, v2, v47
	v_mul_f32_e32 v44, v2, v44
	v_mul_f32_e32 v45, v2, v45
	v_mul_f32_e32 v42, v2, v42
	v_mul_f32_e32 v43, v2, v43
	v_mul_f32_e32 v40, v2, v40
	v_mul_f32_e32 v41, v2, v41
	v_mul_f32_e32 v38, v2, v38
	v_mul_f32_e32 v39, v2, v39
	v_mul_f32_e32 v36, v2, v36
	v_mul_f32_e32 v37, v2, v37
	v_mul_f32_e32 v34, v2, v34
	v_mul_f32_e32 v35, v2, v35
	v_mul_f32_e32 v32, v2, v32
	v_mul_f32_e32 v33, v2, v33
	v_mul_f32_e32 v30, v2, v30
	v_mul_f32_e32 v31, v2, v31
	v_mul_f32_e32 v28, v2, v28
	v_mul_f32_e32 v29, v2, v29
	v_mul_f32_e32 v26, v2, v26
	v_mul_f32_e32 v27, v2, v27
	v_mul_f32_e32 v24, v2, v24
	v_mul_f32_e32 v25, v2, v25
	v_mul_f32_e32 v22, v2, v22
	v_mul_f32_e32 v23, v2, v23
	v_mul_f32_e32 v20, v2, v20
	v_mul_f32_e32 v21, v2, v21
	v_mul_f32_e32 v18, v2, v18
	v_mul_f32_e32 v19, v2, v19
	v_mul_f32_e32 v16, v2, v16
	v_mul_f32_e32 v17, v2, v17
	v_mul_f32_e32 v177, v177, v2

; __device__ __forceinline__ void attn_win(unsigned char* lds, const int unit, const bf16_t* __restrict__ QKG, const bf16_t* __restrict__ Vt, bf16_t* __restrict__ Oout, const float* __restrict__ sink) {
;     ...
;         float mx = fmaxf(p0[0], p1[0]);
; #pragma unroll
;         for (int r = 1; r < 16; ++r) mx = fmaxf(mx, fmaxf(p0[r], p1[r]));
;         mx = fmaxf(mx, __shfl_xor(mx, 32));
;         if (__any(mx > m_run + THR)) { const float mnew = fmaxf(m_run, mx), alpha = __builtin_amdgcn_exp2f(m_run - mnew); m_run = mnew; l_run *= alpha;
; #pragma unroll
;             for (int i = 0; i < 4; ++i)
; #pragma unroll
;                 for (int r = 0; r < 16; ++r) o[i][r] *= alpha; }
.LBB0_622:
	s_nop 10
	v_max_f32_e32 v0, v81, v81
	v_max_f32_e32 v2, v97, v97
	v_max_f32_e32 v0, v2, v0
	v_max_f32_e32 v2, v82, v82
	v_max_f32_e32 v3, v98, v98
	v_max_f32_e32 v2, v3, v2
	v_max_f32_e32 v3, v83, v83
	v_max_f32_e32 v4, v99, v99
	v_max3_f32 v0, v96, v80, v0
	v_max_f32_e32 v3, v4, v3
	v_max3_f32 v0, v0, v2, v3
	v_max_f32_e32 v2, v84, v84
	v_max_f32_e32 v3, v100, v100
	v_max_f32_e32 v2, v3, v2
	v_max_f32_e32 v3, v85, v85
	v_max_f32_e32 v4, v101, v101
	v_max_f32_e32 v3, v4, v3
	v_max3_f32 v0, v0, v2, v3
	v_max_f32_e32 v2, v86, v86
	v_max_f32_e32 v3, v102, v102
	v_max_f32_e32 v2, v3, v2
	v_max_f32_e32 v3, v87, v87
	v_max_f32_e32 v4, v103, v103
	v_max_f32_e32 v3, v4, v3
	v_max3_f32 v0, v0, v2, v3
	v_max_f32_e32 v2, v88, v88
	v_max_f32_e32 v3, v104, v104
	v_max_f32_e32 v2, v3, v2
	v_max_f32_e32 v3, v89, v89
	v_max_f32_e32 v4, v105, v105
	v_max_f32_e32 v3, v4, v3
	v_max3_f32 v0, v0, v2, v3
	v_max_f32_e32 v2, v90, v90
	v_max_f32_e32 v3, v106, v106
	v_max_f32_e32 v2, v3, v2
	v_max_f32_e32 v3, v91, v91
	v_max_f32_e32 v4, v107, v107
	v_max_f32_e32 v3, v4, v3
	v_max3_f32 v0, v0, v2, v3
	v_max_f32_e32 v2, v92, v92
	v_max_f32_e32 v3, v108, v108
	v_max_f32_e32 v2, v3, v2
	v_max_f32_e32 v3, v93, v93
	v_max_f32_e32 v4, v109, v109
	v_max_f32_e32 v3, v4, v3
	v_max3_f32 v0, v0, v2, v3
	v_max_f32_e32 v2, v94, v94
	v_max_f32_e32 v3, v110, v110
	v_max_f32_e32 v2, v3, v2
	v_max_f32_e32 v3, v95, v95
	v_max_f32_e32 v4, v111, v111
	v_max_f32_e32 v3, v4, v3
	v_max3_f32 v0, v0, v2, v3
	v_and_b32_e32 v3, 64, v206
	v_xor_b32_e32 v2, 32, v206
	v_add_u32_e32 v3, 64, v3
	v_cmp_lt_i32_e32 vcc, v2, v3
	s_nop 1
	v_cndmask_b32_e32 v2, v206, v2, vcc
	v_lshlrev_b32_e32 v2, 2, v2
	ds_bpermute_b32 v2, v2, v0
	s_waitcnt lgkmcnt(0)
	v_max_f32_e32 v2, v2, v2
	v_max_f32_e32 v0, v0, v2
	v_add_f32_e32 v2, 0x41000000, v195
	v_cmp_gt_f32_e32 vcc, v0, v2
	s_cbranch_vccz .LBB0_609
	v_max_f32_e32 v0, v0, v0
	v_max_f32_e32 v2, v195, v195
	v_max_f32_e32 v2, v2, v0
	v_sub_f32_e32 v0, v195, v2
	v_exp_f32_e32 v0, v0
	v_mov_b32_e32 v195, v2
	v_mul_f32_e32 v78, v0, v78
	v_mul_f32_e32 v79, v0, v79
	v_mul_f32_e32 v76, v0, v76
	v_mul_f32_e32 v77, v0, v77
	v_mul_f32_e32 v74, v0, v74
	v_mul_f32_e32 v75, v0, v75
	v_mul_f32_e32 v72, v0, v72
	v_mul_f32_e32 v73, v0, v73
	v_mul_f32_e32 v70, v0, v70
	v_mul_f32_e32 v71, v0, v71
	v_mul_f32_e32 v68, v0, v68
	v_mul_f32_e32 v69, v0, v69
	v_mul_f32_e32 v66, v0, v66
	v_mul_f32_e32 v67, v0, v67
	v_mul_f32_e32 v64, v0, v64
	v_mul_f32_e32 v65, v0, v65
	v_mul_f32_e32 v62, v0, v62
	v_mul_f32_e32 v63, v0, v63
	v_mul_f32_e32 v60, v0, v60
	v_mul_f32_e32 v61, v0, v61
	v_mul_f32_e32 v58, v0, v58
	v_mul_f32_e32 v59, v0, v59
	v_mul_f32_e32 v56, v0, v56
	v_mul_f32_e32 v57, v0, v57
	v_mul_f32_e32 v54, v0, v54
	v_mul_f32_e32 v55, v0, v55
	v_mul_f32_e32 v52, v0, v52
	v_mul_f32_e32 v53, v0, v53
	v_mul_f32_e32 v50, v0, v50
	v_mul_f32_e32 v51, v0, v51
	v_mul_f32_e32 v48, v0, v48
	v_mul_f32_e32 v49, v0, v49
	v_mul_f32_e32 v46, v0, v46
	v_mul_f32_e32 v47, v0, v47
	v_mul_f32_e32 v44, v0, v44
	v_mul_f32_e32 v45, v0, v45
	v_mul_f32_e32 v42, v0, v42
	v_mul_f32_e32 v43, v0, v43
	v_mul_f32_e32 v40, v0, v40
	v_mul_f32_e32 v41, v0, v41
	v_mul_f32_e32 v38, v0, v38
	v_mul_f32_e32 v39, v0, v39
	v_mul_f32_e32 v36, v0, v36
	v_mul_f32_e32 v37, v0, v37
	v_mul_f32_e32 v34, v0, v34
	v_mul_f32_e32 v35, v0, v35
	v_mul_f32_e32 v32, v0, v32
	v_mul_f32_e32 v33, v0, v33
	v_mul_f32_e32 v30, v0, v30
	v_mul_f32_e32 v31, v0, v31
	v_mul_f32_e32 v28, v0, v28
	v_mul_f32_e32 v29, v0, v29
	v_mul_f32_e32 v26, v0, v26
	v_mul_f32_e32 v27, v0, v27
	v_mul_f32_e32 v24, v0, v24
	v_mul_f32_e32 v25, v0, v25
	v_mul_f32_e32 v22, v0, v22
	v_mul_f32_e32 v23, v0, v23
	v_mul_f32_e32 v20, v0, v20
	v_mul_f32_e32 v21, v0, v21
	v_mul_f32_e32 v18, v0, v18
	v_mul_f32_e32 v19, v0, v19
	v_mul_f32_e32 v16, v0, v16
	v_mul_f32_e32 v17, v0, v17
	v_mul_f32_e32 v177, v177, v0
	s_branch .LBB0_609
